# deferred-rendezvous barriers: the XCD leader releases its own XCD before its L2 write-back and cross-XCD arrival
# speedup vs baseline: 1.0164x; 1.0033x over previous
.LBB0_505:
	s_andn2_saveexec_b64 s[4:5], s[4:5]
	s_cbranch_execz .LBB0_525
	s_mov_b64 s[4:5], exec
	v_readlane_b32 s12, v255, 40
	s_nop 1
	s_cmp_eq_u32 s12, 0
	s_cbranch_scc1 .Lxd2_glob
	v_readlane_b32 s12, v254, 16
	v_readlane_b32 s13, v254, 17
	v_mov_b32_e32 v0, 1
	s_nop 4
	global_atomic_add v1, v0, s[12:13]
	buffer_wbl2 sc1
	s_waitcnt vmcnt(0)
	v_readlane_b32 s12, v254, 18
	v_readlane_b32 s13, v254, 19
	v_mov_b32_e32 v0, 1
	s_nop 4
	global_atomic_add v0, v1, v0, s[12:13] sc0
	s_waitcnt vmcnt(0)
	v_add_u32_e32 v0, 1, v0
	v_and_b32_e32 v0, 7, v0
	v_cmp_eq_u32_e32 vcc, 0, v0
	s_cbranch_vccz .LBB0_525
	v_readlane_b32 s12, v254, 20
	v_readlane_b32 s13, v254, 21
	v_mov_b32_e32 v0, 1
	s_nop 4
	global_atomic_add v1, v0, s[12:13]
	s_waitcnt vmcnt(0)
	s_branch .LBB0_525
